# attention phase: two-group stagger lengthened to 7 us
# speedup vs baseline: 1.0069x; 1.0069x over previous
; DI void phase_attn1(const Params& p, char* smem) {
;   const int G = gridDim.x;
;   for (int round = 0; round * G < 512; ++round) {
;     const int j = (round & 1) ? (G - 1 - (int)blockIdx.x) : (int)blockIdx.x;
;     const int t = round * G + j;
;     if (t >= 512) continue;
;     const int qt = 15 - (t >> 5), bh = t & 31;
;     mla_item(p, bh >> 3, bh & 7, qt, smem);
;   }
.LBB0_1361:
	s_or_b64 exec, exec, s[0:1]
	s_not_b32 s0, s84
	s_add_i32 s27, s96, s0
	s_add_u32 s24, s22, 0x154c0000
	s_addc_u32 s25, s23, 0
	s_add_u32 s33, s22, 0x184c0000
	s_addc_u32 s40, s23, 0
	s_add_u32 s41, s22, 0x1a4c0000
	s_addc_u32 s44, s23, 0
	s_add_u32 s45, s22, 0x1a6c0000
	s_addc_u32 s46, s23, 0
	s_add_u32 s28, s22, 0x40c0000
	s_movk_i32 s34, 0xff00
	s_addc_u32 s29, s23, 0
	s_mov_b32 s31, 0
	s_movk_i32 s47, 0xc00
	v_mov_b32_e32 v0, 0
	s_mov_b32 s48, 0x2aaaaaab
	s_mov_b32 s35, -1
	s_movk_i32 s49, 0x190
	s_movk_i32 s50, 0x88
	s_movk_i32 s51, 0x6400
	s_mov_b32 s52, 0xf149f2ca
	s_mov_b32 s53, 0x3dd53b94
	s_mov_b32 s54, 0x41000000
	s_mov_b64 s[36:37], 0x20000
	s_mov_b64 s[38:39], 0x2000
	s_movk_i32 s55, 0x3300
	s_mov_b64 s[42:43], 0x80c0a00
	s_mov_b32 s56, 0x80c0000
	v_mov_b32_e32 v199, 0xf149f2ca
	v_mbcnt_hi_u32_b32 v198, -1, v207
	s_mov_b32 s0, 0
	s_mov_b32 s57, 0
	v_readlane_b32 s98, v252, 38
	s_bitcmp1_b32 s98, 6
	s_cbranch_scc0 .Lstag_10
	s_sleep 127
	s_sleep 127
